# Wo-GEMM residual epilogues (both variants) and down-GEMM epilogue: loads issued up front behind counted waits
# speedup vs baseline: 1.0030x; 1.0030x over previous
.LBB0_1024:
	s_ashr_i32 s13, s24, 3
	s_mul_hi_i32 s18, s13, 0xc000
	s_mul_i32 s13, s13, 0xc000
	s_add_u32 s13, s0, s13
	s_addc_u32 s22, s1, s18
	s_lshl_b32 s18, s25, 8
	s_ashr_i32 s19, s18, 31
	s_lshl_b64 s[20:21], s[18:19], 2
	s_add_u32 s20, s13, s20
	s_addc_u32 s21, s22, s21
	s_lshl_b32 s22, s24, 8
	s_ashr_i32 s23, s22, 31
	s_lshl_b64 s[22:23], s[22:23], 11
	s_add_u32 s24, s22, s18
	s_addc_u32 s25, s23, s19
	s_lshl_b64 s[22:23], s[24:25], 1
	s_add_u32 s18, s3, s22
	s_addc_u32 s19, s50, s23
	s_andn2_b64 vcc, exec, s[8:9]
	s_mov_b64 s[26:27], -1
	s_cbranch_vccnz .LBB0_1027
	s_lshl_b64 s[24:25], s[24:25], 2
	v_mov_b32_e32 v0, v147
	v_mov_b32_e32 v142, v146
	s_add_u32 vcc_lo, s97, s24
	s_addc_u32 vcc_hi, s96, s25
	v_lshl_add_u32 v144, v142, 3, s51
	v_lshl_add_u32 v150, v0, 11, s60
	v_add_u32_e32 v0, v144, v150
	v_ashrrev_i32_e32 v145, 31, v144
	v_lshl_add_u64 v[142:143], v[144:145], 2, s[20:21]
	v_lshl_add_u64 v[160:161], v[0:1], 2, vcc
	v_lshlrev_b32_e32 v144, 2, v0
	v_lshlrev_b32_e32 v0, 1, v0
	global_load_dwordx4 v[150:153], v[142:143], off
	global_load_dwordx4 v[154:157], v[142:143], off offset:16
	global_load_dwordx4 v[158:161], v[142:143], off offset:512
	global_load_dwordx4 v[194:197], v[142:143], off offset:528
	s_add_u32 s98, vcc_lo, 0x0
	s_addc_u32 s99, vcc_hi, 0
	global_load_dwordx4 v[168:171], v144, s[98:99]
	global_load_dwordx4 v[172:175], v144, s[98:99] offset:16
	s_add_u32 s98, vcc_lo, 0x0
	s_addc_u32 s99, vcc_hi, 0
	global_load_dwordx4 v[176:179], v144, s[98:99] offset:512
	global_load_dwordx4 v[182:185], v144, s[98:99] offset:528
	s_add_u32 s98, vcc_lo, 0x20000
	s_addc_u32 s99, vcc_hi, 0
	global_load_dwordx4 v[186:189], v144, s[98:99]
	global_load_dwordx4 v[190:193], v144, s[98:99] offset:16
	s_add_u32 s98, vcc_lo, 0x20000
	s_addc_u32 s99, vcc_hi, 0
	global_load_dwordx4 v[204:207], v144, s[98:99] offset:512
	global_load_dwordx4 v[208:211], v144, s[98:99] offset:528
	s_add_u32 s98, vcc_lo, 0x40000
	s_addc_u32 s99, vcc_hi, 0
	global_load_dwordx4 v[216:219], v144, s[98:99]
	global_load_dwordx4 v[220:223], v144, s[98:99] offset:16
	s_add_u32 s98, vcc_lo, 0x40000
	s_addc_u32 s99, vcc_hi, 0
	global_load_dwordx4 v[224:227], v144, s[98:99] offset:512
	global_load_dwordx4 v[228:231], v144, s[98:99] offset:528
	s_waitcnt vmcnt(10)
	v_pk_fma_f32 v[126:127], v[126:127], v[150:151], v[168:169]
	v_pk_fma_f32 v[128:129], v[128:129], v[152:153], v[170:171]
	v_pk_fma_f32 v[122:123], v[122:123], v[154:155], v[172:173]
	v_pk_fma_f32 v[124:125], v[124:125], v[156:157], v[174:175]
	v_cvt_pk_bf16_f32 v126, v126, v127
	v_cvt_pk_bf16_f32 v127, v128, v129
	v_cvt_pk_bf16_f32 v128, v122, v123
	v_cvt_pk_bf16_f32 v129, v124, v125
	s_add_u32 s100, s18, 0x0
	s_addc_u32 s101, s19, 0
	global_store_dwordx4 v0, v[126:129], s[100:101]
	s_add_u32 s98, vcc_lo, 0x60000
	s_addc_u32 s99, vcc_hi, 0
	global_load_dwordx4 v[168:171], v144, s[98:99]
	global_load_dwordx4 v[172:175], v144, s[98:99] offset:16
	s_waitcnt vmcnt(11)
	v_pk_fma_f32 v[118:119], v[118:119], v[158:159], v[176:177]
	v_pk_fma_f32 v[120:121], v[120:121], v[160:161], v[178:179]
	v_pk_fma_f32 v[114:115], v[114:115], v[194:195], v[182:183]
	v_pk_fma_f32 v[116:117], v[116:117], v[196:197], v[184:185]
	v_cvt_pk_bf16_f32 v118, v118, v119
	v_cvt_pk_bf16_f32 v119, v120, v121
	v_cvt_pk_bf16_f32 v120, v114, v115
	v_cvt_pk_bf16_f32 v121, v116, v117
	global_store_dwordx4 v0, v[118:121], s[100:101] offset:256
	s_add_u32 s98, vcc_lo, 0x60000
	s_addc_u32 s99, vcc_hi, 0
	global_load_dwordx4 v[176:179], v144, s[98:99] offset:512
	global_load_dwordx4 v[182:185], v144, s[98:99] offset:528
	s_waitcnt vmcnt(12)
	v_pk_fma_f32 v[110:111], v[110:111], v[150:151], v[186:187]
	v_pk_fma_f32 v[112:113], v[112:113], v[152:153], v[188:189]
	v_pk_fma_f32 v[106:107], v[106:107], v[154:155], v[190:191]
	v_pk_fma_f32 v[108:109], v[108:109], v[156:157], v[192:193]
	v_cvt_pk_bf16_f32 v110, v110, v111
	v_cvt_pk_bf16_f32 v111, v112, v113
	v_cvt_pk_bf16_f32 v112, v106, v107
	v_cvt_pk_bf16_f32 v113, v108, v109
	s_add_u32 s100, s18, 0x10000
	s_addc_u32 s101, s19, 0
	global_store_dwordx4 v0, v[110:113], s[100:101]
	s_add_u32 s98, vcc_lo, 0x100000
	s_addc_u32 s99, vcc_hi, 0
	global_load_dwordx4 v[186:189], v144, s[98:99]
	global_load_dwordx4 v[190:193], v144, s[98:99] offset:16
	s_waitcnt vmcnt(13)
	v_pk_fma_f32 v[102:103], v[102:103], v[158:159], v[204:205]
	v_pk_fma_f32 v[104:105], v[104:105], v[160:161], v[206:207]
	v_pk_fma_f32 v[98:99], v[98:99], v[194:195], v[208:209]
	v_pk_fma_f32 v[100:101], v[100:101], v[196:197], v[210:211]
	v_cvt_pk_bf16_f32 v102, v102, v103
	v_cvt_pk_bf16_f32 v103, v104, v105
	v_cvt_pk_bf16_f32 v104, v98, v99
	v_cvt_pk_bf16_f32 v105, v100, v101
	global_store_dwordx4 v0, v[102:105], s[100:101] offset:256
	s_add_u32 s98, vcc_lo, 0x100000
	s_addc_u32 s99, vcc_hi, 0
	global_load_dwordx4 v[204:207], v144, s[98:99] offset:512
	global_load_dwordx4 v[208:211], v144, s[98:99] offset:528
	s_waitcnt vmcnt(14)
	v_pk_fma_f32 v[94:95], v[94:95], v[150:151], v[216:217]
	v_pk_fma_f32 v[96:97], v[96:97], v[152:153], v[218:219]
	v_pk_fma_f32 v[90:91], v[90:91], v[154:155], v[220:221]
	v_pk_fma_f32 v[92:93], v[92:93], v[156:157], v[222:223]
	v_cvt_pk_bf16_f32 v94, v94, v95
	v_cvt_pk_bf16_f32 v95, v96, v97
	v_cvt_pk_bf16_f32 v96, v90, v91
	v_cvt_pk_bf16_f32 v97, v92, v93
	s_add_u32 s100, s18, 0x20000
	s_addc_u32 s101, s19, 0
	global_store_dwordx4 v0, v[94:97], s[100:101]
	s_add_u32 s98, vcc_lo, 0x120000
	s_addc_u32 s99, vcc_hi, 0
	global_load_dwordx4 v[216:219], v144, s[98:99]
	global_load_dwordx4 v[220:223], v144, s[98:99] offset:16
	s_waitcnt vmcnt(15)
	v_pk_fma_f32 v[86:87], v[86:87], v[158:159], v[224:225]
	v_pk_fma_f32 v[88:89], v[88:89], v[160:161], v[226:227]
	v_pk_fma_f32 v[82:83], v[82:83], v[194:195], v[228:229]
	v_pk_fma_f32 v[84:85], v[84:85], v[196:197], v[230:231]
	v_cvt_pk_bf16_f32 v86, v86, v87
	v_cvt_pk_bf16_f32 v87, v88, v89
	v_cvt_pk_bf16_f32 v88, v82, v83
	v_cvt_pk_bf16_f32 v89, v84, v85
	global_store_dwordx4 v0, v[86:89], s[100:101] offset:256
	s_add_u32 s98, vcc_lo, 0x120000
	s_addc_u32 s99, vcc_hi, 0
	global_load_dwordx4 v[224:227], v144, s[98:99] offset:512
	global_load_dwordx4 v[228:231], v144, s[98:99] offset:528
	s_waitcnt vmcnt(15)
	v_pk_fma_f32 v[78:79], v[78:79], v[150:151], v[168:169]
	v_pk_fma_f32 v[80:81], v[80:81], v[152:153], v[170:171]
	v_pk_fma_f32 v[74:75], v[74:75], v[154:155], v[172:173]
	v_pk_fma_f32 v[76:77], v[76:77], v[156:157], v[174:175]
	v_cvt_pk_bf16_f32 v78, v78, v79
	v_cvt_pk_bf16_f32 v79, v80, v81
	v_cvt_pk_bf16_f32 v80, v74, v75
	v_cvt_pk_bf16_f32 v81, v76, v77
	s_add_u32 s100, s18, 0x30000
	s_addc_u32 s101, s19, 0
	global_store_dwordx4 v0, v[78:81], s[100:101]
	s_add_u32 s98, vcc_lo, 0x140000
	s_addc_u32 s99, vcc_hi, 0
	global_load_dwordx4 v[168:171], v144, s[98:99]
	global_load_dwordx4 v[172:175], v144, s[98:99] offset:16
	s_waitcnt vmcnt(15)
	v_pk_fma_f32 v[70:71], v[70:71], v[158:159], v[176:177]
	v_pk_fma_f32 v[72:73], v[72:73], v[160:161], v[178:179]
	v_pk_fma_f32 v[66:67], v[66:67], v[194:195], v[182:183]
	v_pk_fma_f32 v[68:69], v[68:69], v[196:197], v[184:185]
	v_cvt_pk_bf16_f32 v70, v70, v71
	v_cvt_pk_bf16_f32 v71, v72, v73
	v_cvt_pk_bf16_f32 v72, v66, v67
	v_cvt_pk_bf16_f32 v73, v68, v69
	global_store_dwordx4 v0, v[70:73], s[100:101] offset:256
	s_add_u32 s98, vcc_lo, 0x140000
	s_addc_u32 s99, vcc_hi, 0
	global_load_dwordx4 v[176:179], v144, s[98:99] offset:512
	global_load_dwordx4 v[182:185], v144, s[98:99] offset:528
	s_waitcnt vmcnt(15)
	v_pk_fma_f32 v[62:63], v[62:63], v[150:151], v[186:187]
	v_pk_fma_f32 v[64:65], v[64:65], v[152:153], v[188:189]
	v_pk_fma_f32 v[58:59], v[58:59], v[154:155], v[190:191]
	v_pk_fma_f32 v[60:61], v[60:61], v[156:157], v[192:193]
	v_cvt_pk_bf16_f32 v62, v62, v63
	v_cvt_pk_bf16_f32 v63, v64, v65
	v_cvt_pk_bf16_f32 v64, v58, v59
	v_cvt_pk_bf16_f32 v65, v60, v61
	s_add_u32 s100, s18, 0x80000
	s_addc_u32 s101, s19, 0
	global_store_dwordx4 v0, v[62:65], s[100:101]
	s_add_u32 s98, vcc_lo, 0x160000
	s_addc_u32 s99, vcc_hi, 0
	global_load_dwordx4 v[186:189], v144, s[98:99]
	global_load_dwordx4 v[190:193], v144, s[98:99] offset:16
	s_waitcnt vmcnt(15)
	v_pk_fma_f32 v[54:55], v[54:55], v[158:159], v[204:205]
	v_pk_fma_f32 v[56:57], v[56:57], v[160:161], v[206:207]
	v_pk_fma_f32 v[50:51], v[50:51], v[194:195], v[208:209]
	v_pk_fma_f32 v[52:53], v[52:53], v[196:197], v[210:211]
	v_cvt_pk_bf16_f32 v54, v54, v55
	v_cvt_pk_bf16_f32 v55, v56, v57
	v_cvt_pk_bf16_f32 v56, v50, v51
	v_cvt_pk_bf16_f32 v57, v52, v53
	global_store_dwordx4 v0, v[54:57], s[100:101] offset:256
	s_add_u32 s98, vcc_lo, 0x160000
	s_addc_u32 s99, vcc_hi, 0
	global_load_dwordx4 v[204:207], v144, s[98:99] offset:512
	global_load_dwordx4 v[208:211], v144, s[98:99] offset:528
	s_waitcnt vmcnt(15)
	v_pk_fma_f32 v[46:47], v[46:47], v[150:151], v[216:217]
	v_pk_fma_f32 v[48:49], v[48:49], v[152:153], v[218:219]
	v_pk_fma_f32 v[42:43], v[42:43], v[154:155], v[220:221]
	v_pk_fma_f32 v[44:45], v[44:45], v[156:157], v[222:223]
	v_cvt_pk_bf16_f32 v46, v46, v47
	v_cvt_pk_bf16_f32 v47, v48, v49
	v_cvt_pk_bf16_f32 v48, v42, v43
	v_cvt_pk_bf16_f32 v49, v44, v45
	s_add_u32 s100, s18, 0x90000
	s_addc_u32 s101, s19, 0
	global_store_dwordx4 v0, v[46:49], s[100:101]
	s_waitcnt vmcnt(13)
	v_pk_fma_f32 v[38:39], v[38:39], v[158:159], v[224:225]
	v_pk_fma_f32 v[40:41], v[40:41], v[160:161], v[226:227]
	v_pk_fma_f32 v[34:35], v[34:35], v[194:195], v[228:229]
	v_pk_fma_f32 v[36:37], v[36:37], v[196:197], v[230:231]
	v_cvt_pk_bf16_f32 v38, v38, v39
	v_cvt_pk_bf16_f32 v39, v40, v41
	v_cvt_pk_bf16_f32 v40, v34, v35
	v_cvt_pk_bf16_f32 v41, v36, v37
	global_store_dwordx4 v0, v[38:41], s[100:101] offset:256
	s_waitcnt vmcnt(11)
	v_pk_fma_f32 v[30:31], v[30:31], v[150:151], v[168:169]
	v_pk_fma_f32 v[32:33], v[32:33], v[152:153], v[170:171]
	v_pk_fma_f32 v[26:27], v[26:27], v[154:155], v[172:173]
	v_pk_fma_f32 v[28:29], v[28:29], v[156:157], v[174:175]
	v_cvt_pk_bf16_f32 v30, v30, v31
	v_cvt_pk_bf16_f32 v31, v32, v33
	v_cvt_pk_bf16_f32 v32, v26, v27
	v_cvt_pk_bf16_f32 v33, v28, v29
	s_add_u32 s100, s18, 0xa0000
	s_addc_u32 s101, s19, 0
	global_store_dwordx4 v0, v[30:33], s[100:101]
	s_waitcnt vmcnt(9)
	v_pk_fma_f32 v[22:23], v[22:23], v[158:159], v[176:177]
	v_pk_fma_f32 v[24:25], v[24:25], v[160:161], v[178:179]
	v_pk_fma_f32 v[18:19], v[18:19], v[194:195], v[182:183]
	v_pk_fma_f32 v[20:21], v[20:21], v[196:197], v[184:185]
	v_cvt_pk_bf16_f32 v22, v22, v23
	v_cvt_pk_bf16_f32 v23, v24, v25
	v_cvt_pk_bf16_f32 v24, v18, v19
	v_cvt_pk_bf16_f32 v25, v20, v21
	global_store_dwordx4 v0, v[22:25], s[100:101] offset:256
	s_waitcnt vmcnt(7)
	v_pk_fma_f32 v[14:15], v[14:15], v[150:151], v[186:187]
	v_pk_fma_f32 v[16:17], v[16:17], v[152:153], v[188:189]
	v_pk_fma_f32 v[10:11], v[10:11], v[154:155], v[190:191]
	v_pk_fma_f32 v[12:13], v[12:13], v[156:157], v[192:193]
	v_cvt_pk_bf16_f32 v14, v14, v15
	v_cvt_pk_bf16_f32 v15, v16, v17
	v_cvt_pk_bf16_f32 v16, v10, v11
	v_cvt_pk_bf16_f32 v17, v12, v13
	s_add_u32 s100, s18, 0xb0000
	s_addc_u32 s101, s19, 0
	global_store_dwordx4 v0, v[14:17], s[100:101]
	s_waitcnt vmcnt(5)
	v_pk_fma_f32 v[6:7], v[6:7], v[158:159], v[204:205]
	v_pk_fma_f32 v[8:9], v[8:9], v[160:161], v[206:207]
	v_pk_fma_f32 v[2:3], v[2:3], v[194:195], v[208:209]
	v_pk_fma_f32 v[4:5], v[4:5], v[196:197], v[210:211]
	v_cvt_pk_bf16_f32 v6, v6, v7
	v_cvt_pk_bf16_f32 v7, v8, v9
	v_cvt_pk_bf16_f32 v8, v2, v3
	v_cvt_pk_bf16_f32 v9, v4, v5
	global_store_dwordx4 v0, v[6:9], s[100:101] offset:256
	s_cbranch_execz .LBB0_1028

.LBB0_1028:
	v_mov_b32_e32 v0, v147
	v_mov_b32_e32 v142, v146
	s_add_u32 vcc_lo, s46, s22
	v_lshl_add_u32 v144, v142, 3, s51
	v_lshl_add_u32 v150, v0, 11, s60
	v_add_u32_e32 v0, v144, v150
	s_addc_u32 vcc_hi, s47, s23
	v_ashrrev_i32_e32 v145, 31, v144
	v_lshlrev_b64 v[160:161], 1, v[0:1]
	v_lshl_add_u64 v[142:143], v[144:145], 2, s[20:21]
	v_lshl_add_u64 v[168:169], vcc, 0, v[160:161]
	v_lshlrev_b32_e32 v0, 1, v0
	global_load_dwordx4 v[150:153], v[142:143], off
	global_load_dwordx4 v[154:157], v[142:143], off offset:16
	global_load_dwordx4 v[158:161], v[142:143], off offset:512
	global_load_dwordx4 v[196:199], v[142:143], off offset:528
	s_add_u32 s98, vcc_lo, 0x0
	s_addc_u32 s99, vcc_hi, 0
	global_load_dwordx4 v[168:171], v0, s[98:99]
	s_add_u32 s98, vcc_lo, 0x0
	s_addc_u32 s99, vcc_hi, 0
	global_load_dwordx4 v[172:175], v0, s[98:99] offset:256
	s_add_u32 s98, vcc_lo, 0x10000
	s_addc_u32 s99, vcc_hi, 0
	global_load_dwordx4 v[176:179], v0, s[98:99]
	s_add_u32 s98, vcc_lo, 0x10000
	s_addc_u32 s99, vcc_hi, 0
	global_load_dwordx4 v[182:185], v0, s[98:99] offset:256
	s_add_u32 s98, vcc_lo, 0x20000
	s_addc_u32 s99, vcc_hi, 0
	global_load_dwordx4 v[186:189], v0, s[98:99]
	s_add_u32 s98, vcc_lo, 0x20000
	s_addc_u32 s99, vcc_hi, 0
	global_load_dwordx4 v[190:193], v0, s[98:99] offset:256
	s_add_u32 s98, vcc_lo, 0x30000
	s_addc_u32 s99, vcc_hi, 0
	global_load_dwordx4 v[204:207], v0, s[98:99]
	s_add_u32 s98, vcc_lo, 0x30000
	s_addc_u32 s99, vcc_hi, 0
	global_load_dwordx4 v[208:211], v0, s[98:99] offset:256
	s_add_u32 s98, vcc_lo, 0x80000
	s_addc_u32 s99, vcc_hi, 0
	global_load_dwordx4 v[216:219], v0, s[98:99]
	s_add_u32 s98, vcc_lo, 0x80000
	s_addc_u32 s99, vcc_hi, 0
	global_load_dwordx4 v[220:223], v0, s[98:99] offset:256
	s_waitcnt vmcnt(9)
	v_lshlrev_b32_e32 v226, 16, v168
	v_and_b32_e32 v227, 0xffff0000, v168
	v_lshlrev_b32_e32 v228, 16, v169
	v_and_b32_e32 v229, 0xffff0000, v169
	v_lshlrev_b32_e32 v230, 16, v170
	v_and_b32_e32 v231, 0xffff0000, v170
	v_lshlrev_b32_e32 v232, 16, v171
	v_and_b32_e32 v233, 0xffff0000, v171
	v_pk_fma_f32 v[126:127], v[126:127], v[150:151], v[226:227]
	v_pk_fma_f32 v[128:129], v[128:129], v[152:153], v[228:229]
	v_pk_fma_f32 v[122:123], v[122:123], v[154:155], v[230:231]
	v_pk_fma_f32 v[124:125], v[124:125], v[156:157], v[232:233]
	v_cvt_pk_bf16_f32 v126, v126, v127
	v_cvt_pk_bf16_f32 v127, v128, v129
	v_cvt_pk_bf16_f32 v128, v122, v123
	v_cvt_pk_bf16_f32 v129, v124, v125
	s_add_u32 s100, s18, 0x0
	s_addc_u32 s101, s19, 0
	global_store_dwordx4 v0, v[126:129], s[100:101]
	s_add_u32 s98, vcc_lo, 0x90000
	s_addc_u32 s99, vcc_hi, 0
	global_load_dwordx4 v[122:125], v0, s[98:99]
	s_waitcnt vmcnt(10)
	v_lshlrev_b32_e32 v226, 16, v172
	v_and_b32_e32 v227, 0xffff0000, v172
	v_lshlrev_b32_e32 v228, 16, v173
	v_and_b32_e32 v229, 0xffff0000, v173
	v_lshlrev_b32_e32 v230, 16, v174
	v_and_b32_e32 v231, 0xffff0000, v174
	v_lshlrev_b32_e32 v232, 16, v175
	v_and_b32_e32 v233, 0xffff0000, v175
	v_pk_fma_f32 v[118:119], v[118:119], v[158:159], v[226:227]
	v_pk_fma_f32 v[120:121], v[120:121], v[160:161], v[228:229]
	v_pk_fma_f32 v[114:115], v[114:115], v[196:197], v[230:231]
	v_pk_fma_f32 v[116:117], v[116:117], v[198:199], v[232:233]
	v_cvt_pk_bf16_f32 v118, v118, v119
	v_cvt_pk_bf16_f32 v119, v120, v121
	v_cvt_pk_bf16_f32 v120, v114, v115
	v_cvt_pk_bf16_f32 v121, v116, v117
	global_store_dwordx4 v0, v[118:121], s[100:101] offset:256
	s_add_u32 s98, vcc_lo, 0x90000
	s_addc_u32 s99, vcc_hi, 0
	global_load_dwordx4 v[114:117], v0, s[98:99] offset:256
	s_waitcnt vmcnt(11)
	v_lshlrev_b32_e32 v226, 16, v176
	v_and_b32_e32 v227, 0xffff0000, v176
	v_lshlrev_b32_e32 v228, 16, v177
	v_and_b32_e32 v229, 0xffff0000, v177
	v_lshlrev_b32_e32 v230, 16, v178
	v_and_b32_e32 v231, 0xffff0000, v178
	v_lshlrev_b32_e32 v232, 16, v179
	v_and_b32_e32 v233, 0xffff0000, v179
	v_pk_fma_f32 v[110:111], v[110:111], v[150:151], v[226:227]
	v_pk_fma_f32 v[112:113], v[112:113], v[152:153], v[228:229]
	v_pk_fma_f32 v[106:107], v[106:107], v[154:155], v[230:231]
	v_pk_fma_f32 v[108:109], v[108:109], v[156:157], v[232:233]
	v_cvt_pk_bf16_f32 v110, v110, v111
	v_cvt_pk_bf16_f32 v111, v112, v113
	v_cvt_pk_bf16_f32 v112, v106, v107
	v_cvt_pk_bf16_f32 v113, v108, v109
	s_add_u32 s100, s18, 0x10000
	s_addc_u32 s101, s19, 0
	global_store_dwordx4 v0, v[110:113], s[100:101]
	s_add_u32 s98, vcc_lo, 0xa0000
	s_addc_u32 s99, vcc_hi, 0
	global_load_dwordx4 v[106:109], v0, s[98:99]
	s_waitcnt vmcnt(12)
	v_lshlrev_b32_e32 v226, 16, v182
	v_and_b32_e32 v227, 0xffff0000, v182
	v_lshlrev_b32_e32 v228, 16, v183
	v_and_b32_e32 v229, 0xffff0000, v183
	v_lshlrev_b32_e32 v230, 16, v184
	v_and_b32_e32 v231, 0xffff0000, v184
	v_lshlrev_b32_e32 v232, 16, v185
	v_and_b32_e32 v233, 0xffff0000, v185
	v_pk_fma_f32 v[102:103], v[102:103], v[158:159], v[226:227]
	v_pk_fma_f32 v[104:105], v[104:105], v[160:161], v[228:229]
	v_pk_fma_f32 v[98:99], v[98:99], v[196:197], v[230:231]
	v_pk_fma_f32 v[100:101], v[100:101], v[198:199], v[232:233]
	v_cvt_pk_bf16_f32 v102, v102, v103
	v_cvt_pk_bf16_f32 v103, v104, v105
	v_cvt_pk_bf16_f32 v104, v98, v99
	v_cvt_pk_bf16_f32 v105, v100, v101
	global_store_dwordx4 v0, v[102:105], s[100:101] offset:256
	s_add_u32 s98, vcc_lo, 0xa0000
	s_addc_u32 s99, vcc_hi, 0
	global_load_dwordx4 v[98:101], v0, s[98:99] offset:256
	s_waitcnt vmcnt(13)
	v_lshlrev_b32_e32 v226, 16, v186
	v_and_b32_e32 v227, 0xffff0000, v186
	v_lshlrev_b32_e32 v228, 16, v187
	v_and_b32_e32 v229, 0xffff0000, v187
	v_lshlrev_b32_e32 v230, 16, v188
	v_and_b32_e32 v231, 0xffff0000, v188
	v_lshlrev_b32_e32 v232, 16, v189
	v_and_b32_e32 v233, 0xffff0000, v189
	v_pk_fma_f32 v[94:95], v[94:95], v[150:151], v[226:227]
	v_pk_fma_f32 v[96:97], v[96:97], v[152:153], v[228:229]
	v_pk_fma_f32 v[90:91], v[90:91], v[154:155], v[230:231]
	v_pk_fma_f32 v[92:93], v[92:93], v[156:157], v[232:233]
	v_cvt_pk_bf16_f32 v94, v94, v95
	v_cvt_pk_bf16_f32 v95, v96, v97
	v_cvt_pk_bf16_f32 v96, v90, v91
	v_cvt_pk_bf16_f32 v97, v92, v93
	s_add_u32 s100, s18, 0x20000
	s_addc_u32 s101, s19, 0
	global_store_dwordx4 v0, v[94:97], s[100:101]
	s_add_u32 s98, vcc_lo, 0xb0000
	s_addc_u32 s99, vcc_hi, 0
	global_load_dwordx4 v[90:93], v0, s[98:99]
	s_waitcnt vmcnt(14)
	v_lshlrev_b32_e32 v226, 16, v190
	v_and_b32_e32 v227, 0xffff0000, v190
	v_lshlrev_b32_e32 v228, 16, v191
	v_and_b32_e32 v229, 0xffff0000, v191
	v_lshlrev_b32_e32 v230, 16, v192
	v_and_b32_e32 v231, 0xffff0000, v192
	v_lshlrev_b32_e32 v232, 16, v193
	v_and_b32_e32 v233, 0xffff0000, v193
	v_pk_fma_f32 v[86:87], v[86:87], v[158:159], v[226:227]
	v_pk_fma_f32 v[88:89], v[88:89], v[160:161], v[228:229]
	v_pk_fma_f32 v[82:83], v[82:83], v[196:197], v[230:231]
	v_pk_fma_f32 v[84:85], v[84:85], v[198:199], v[232:233]
	v_cvt_pk_bf16_f32 v86, v86, v87
	v_cvt_pk_bf16_f32 v87, v88, v89
	v_cvt_pk_bf16_f32 v88, v82, v83
	v_cvt_pk_bf16_f32 v89, v84, v85
	global_store_dwordx4 v0, v[86:89], s[100:101] offset:256
	s_add_u32 s98, vcc_lo, 0xb0000
	s_addc_u32 s99, vcc_hi, 0
	global_load_dwordx4 v[82:85], v0, s[98:99] offset:256
	s_waitcnt vmcnt(15)
	v_lshlrev_b32_e32 v226, 16, v204
	v_and_b32_e32 v227, 0xffff0000, v204
	v_lshlrev_b32_e32 v228, 16, v205
	v_and_b32_e32 v229, 0xffff0000, v205
	v_lshlrev_b32_e32 v230, 16, v206
	v_and_b32_e32 v231, 0xffff0000, v206
	v_lshlrev_b32_e32 v232, 16, v207
	v_and_b32_e32 v233, 0xffff0000, v207
	v_pk_fma_f32 v[78:79], v[78:79], v[150:151], v[226:227]
	v_pk_fma_f32 v[80:81], v[80:81], v[152:153], v[228:229]
	v_pk_fma_f32 v[74:75], v[74:75], v[154:155], v[230:231]
	v_pk_fma_f32 v[76:77], v[76:77], v[156:157], v[232:233]
	v_cvt_pk_bf16_f32 v78, v78, v79
	v_cvt_pk_bf16_f32 v79, v80, v81
	v_cvt_pk_bf16_f32 v80, v74, v75
	v_cvt_pk_bf16_f32 v81, v76, v77
	s_add_u32 s100, s18, 0x30000
	s_addc_u32 s101, s19, 0
	global_store_dwordx4 v0, v[78:81], s[100:101]
	s_waitcnt vmcnt(15)
	v_lshlrev_b32_e32 v226, 16, v208
	v_and_b32_e32 v227, 0xffff0000, v208
	v_lshlrev_b32_e32 v228, 16, v209
	v_and_b32_e32 v229, 0xffff0000, v209
	v_lshlrev_b32_e32 v230, 16, v210
	v_and_b32_e32 v231, 0xffff0000, v210
	v_lshlrev_b32_e32 v232, 16, v211
	v_and_b32_e32 v233, 0xffff0000, v211
	v_pk_fma_f32 v[70:71], v[70:71], v[158:159], v[226:227]
	v_pk_fma_f32 v[72:73], v[72:73], v[160:161], v[228:229]
	v_pk_fma_f32 v[66:67], v[66:67], v[196:197], v[230:231]
	v_pk_fma_f32 v[68:69], v[68:69], v[198:199], v[232:233]
	v_cvt_pk_bf16_f32 v70, v70, v71
	v_cvt_pk_bf16_f32 v71, v72, v73
	v_cvt_pk_bf16_f32 v72, v66, v67
	v_cvt_pk_bf16_f32 v73, v68, v69
	global_store_dwordx4 v0, v[70:73], s[100:101] offset:256
	s_waitcnt vmcnt(15)
	v_lshlrev_b32_e32 v226, 16, v216
	v_and_b32_e32 v227, 0xffff0000, v216
	v_lshlrev_b32_e32 v228, 16, v217
	v_and_b32_e32 v229, 0xffff0000, v217
	v_lshlrev_b32_e32 v230, 16, v218
	v_and_b32_e32 v231, 0xffff0000, v218
	v_lshlrev_b32_e32 v232, 16, v219
	v_and_b32_e32 v233, 0xffff0000, v219
	v_pk_fma_f32 v[62:63], v[62:63], v[150:151], v[226:227]
	v_pk_fma_f32 v[64:65], v[64:65], v[152:153], v[228:229]
	v_pk_fma_f32 v[58:59], v[58:59], v[154:155], v[230:231]
	v_pk_fma_f32 v[60:61], v[60:61], v[156:157], v[232:233]
	v_cvt_pk_bf16_f32 v62, v62, v63
	v_cvt_pk_bf16_f32 v63, v64, v65
	v_cvt_pk_bf16_f32 v64, v58, v59
	v_cvt_pk_bf16_f32 v65, v60, v61
	s_add_u32 s100, s18, 0x80000
	s_addc_u32 s101, s19, 0
	global_store_dwordx4 v0, v[62:65], s[100:101]
	s_waitcnt vmcnt(15)
	v_lshlrev_b32_e32 v226, 16, v220
	v_and_b32_e32 v227, 0xffff0000, v220
	v_lshlrev_b32_e32 v228, 16, v221
	v_and_b32_e32 v229, 0xffff0000, v221
	v_lshlrev_b32_e32 v230, 16, v222
	v_and_b32_e32 v231, 0xffff0000, v222
	v_lshlrev_b32_e32 v232, 16, v223
	v_and_b32_e32 v233, 0xffff0000, v223
	v_pk_fma_f32 v[54:55], v[54:55], v[158:159], v[226:227]
	v_pk_fma_f32 v[56:57], v[56:57], v[160:161], v[228:229]
	v_pk_fma_f32 v[50:51], v[50:51], v[196:197], v[230:231]
	v_pk_fma_f32 v[52:53], v[52:53], v[198:199], v[232:233]
	v_cvt_pk_bf16_f32 v54, v54, v55
	v_cvt_pk_bf16_f32 v55, v56, v57
	v_cvt_pk_bf16_f32 v56, v50, v51
	v_cvt_pk_bf16_f32 v57, v52, v53
	global_store_dwordx4 v0, v[54:57], s[100:101] offset:256
	s_waitcnt vmcnt(14)
	v_lshlrev_b32_e32 v226, 16, v122
	v_and_b32_e32 v227, 0xffff0000, v122
	v_lshlrev_b32_e32 v228, 16, v123
	v_and_b32_e32 v229, 0xffff0000, v123
	v_lshlrev_b32_e32 v230, 16, v124
	v_and_b32_e32 v231, 0xffff0000, v124
	v_lshlrev_b32_e32 v232, 16, v125
	v_and_b32_e32 v233, 0xffff0000, v125
	v_pk_fma_f32 v[46:47], v[46:47], v[150:151], v[226:227]
	v_pk_fma_f32 v[48:49], v[48:49], v[152:153], v[228:229]
	v_pk_fma_f32 v[42:43], v[42:43], v[154:155], v[230:231]
	v_pk_fma_f32 v[44:45], v[44:45], v[156:157], v[232:233]
	v_cvt_pk_bf16_f32 v46, v46, v47
	v_cvt_pk_bf16_f32 v47, v48, v49
	v_cvt_pk_bf16_f32 v48, v42, v43
	v_cvt_pk_bf16_f32 v49, v44, v45
	s_add_u32 s100, s18, 0x90000
	s_addc_u32 s101, s19, 0
	global_store_dwordx4 v0, v[46:49], s[100:101]
	s_waitcnt vmcnt(13)
	v_lshlrev_b32_e32 v226, 16, v114
	v_and_b32_e32 v227, 0xffff0000, v114
	v_lshlrev_b32_e32 v228, 16, v115
	v_and_b32_e32 v229, 0xffff0000, v115
	v_lshlrev_b32_e32 v230, 16, v116
	v_and_b32_e32 v231, 0xffff0000, v116
	v_lshlrev_b32_e32 v232, 16, v117
	v_and_b32_e32 v233, 0xffff0000, v117
	v_pk_fma_f32 v[38:39], v[38:39], v[158:159], v[226:227]
	v_pk_fma_f32 v[40:41], v[40:41], v[160:161], v[228:229]
	v_pk_fma_f32 v[34:35], v[34:35], v[196:197], v[230:231]
	v_pk_fma_f32 v[36:37], v[36:37], v[198:199], v[232:233]
	v_cvt_pk_bf16_f32 v38, v38, v39
	v_cvt_pk_bf16_f32 v39, v40, v41
	v_cvt_pk_bf16_f32 v40, v34, v35
	v_cvt_pk_bf16_f32 v41, v36, v37
	global_store_dwordx4 v0, v[38:41], s[100:101] offset:256
	s_waitcnt vmcnt(12)
	v_lshlrev_b32_e32 v226, 16, v106
	v_and_b32_e32 v227, 0xffff0000, v106
	v_lshlrev_b32_e32 v228, 16, v107
	v_and_b32_e32 v229, 0xffff0000, v107
	v_lshlrev_b32_e32 v230, 16, v108
	v_and_b32_e32 v231, 0xffff0000, v108
	v_lshlrev_b32_e32 v232, 16, v109
	v_and_b32_e32 v233, 0xffff0000, v109
	v_pk_fma_f32 v[30:31], v[30:31], v[150:151], v[226:227]
	v_pk_fma_f32 v[32:33], v[32:33], v[152:153], v[228:229]
	v_pk_fma_f32 v[26:27], v[26:27], v[154:155], v[230:231]
	v_pk_fma_f32 v[28:29], v[28:29], v[156:157], v[232:233]
	v_cvt_pk_bf16_f32 v30, v30, v31
	v_cvt_pk_bf16_f32 v31, v32, v33
	v_cvt_pk_bf16_f32 v32, v26, v27
	v_cvt_pk_bf16_f32 v33, v28, v29
	s_add_u32 s100, s18, 0xa0000
	s_addc_u32 s101, s19, 0
	global_store_dwordx4 v0, v[30:33], s[100:101]
	s_waitcnt vmcnt(11)
	v_lshlrev_b32_e32 v226, 16, v98
	v_and_b32_e32 v227, 0xffff0000, v98
	v_lshlrev_b32_e32 v228, 16, v99
	v_and_b32_e32 v229, 0xffff0000, v99
	v_lshlrev_b32_e32 v230, 16, v100
	v_and_b32_e32 v231, 0xffff0000, v100
	v_lshlrev_b32_e32 v232, 16, v101
	v_and_b32_e32 v233, 0xffff0000, v101
	v_pk_fma_f32 v[22:23], v[22:23], v[158:159], v[226:227]
	v_pk_fma_f32 v[24:25], v[24:25], v[160:161], v[228:229]
	v_pk_fma_f32 v[18:19], v[18:19], v[196:197], v[230:231]
	v_pk_fma_f32 v[20:21], v[20:21], v[198:199], v[232:233]
	v_cvt_pk_bf16_f32 v22, v22, v23
	v_cvt_pk_bf16_f32 v23, v24, v25
	v_cvt_pk_bf16_f32 v24, v18, v19
	v_cvt_pk_bf16_f32 v25, v20, v21
	global_store_dwordx4 v0, v[22:25], s[100:101] offset:256
	s_waitcnt vmcnt(10)
	v_lshlrev_b32_e32 v226, 16, v90
	v_and_b32_e32 v227, 0xffff0000, v90
	v_lshlrev_b32_e32 v228, 16, v91
	v_and_b32_e32 v229, 0xffff0000, v91
	v_lshlrev_b32_e32 v230, 16, v92
	v_and_b32_e32 v231, 0xffff0000, v92
	v_lshlrev_b32_e32 v232, 16, v93
	v_and_b32_e32 v233, 0xffff0000, v93
	v_pk_fma_f32 v[14:15], v[14:15], v[150:151], v[226:227]
	v_pk_fma_f32 v[16:17], v[16:17], v[152:153], v[228:229]
	v_pk_fma_f32 v[10:11], v[10:11], v[154:155], v[230:231]
	v_pk_fma_f32 v[12:13], v[12:13], v[156:157], v[232:233]
	v_cvt_pk_bf16_f32 v14, v14, v15
	v_cvt_pk_bf16_f32 v15, v16, v17
	v_cvt_pk_bf16_f32 v16, v10, v11
	v_cvt_pk_bf16_f32 v17, v12, v13
	s_add_u32 s100, s18, 0xb0000
	s_addc_u32 s101, s19, 0
	global_store_dwordx4 v0, v[14:17], s[100:101]
	s_waitcnt vmcnt(9)
	v_lshlrev_b32_e32 v226, 16, v82
	v_and_b32_e32 v227, 0xffff0000, v82
	v_lshlrev_b32_e32 v228, 16, v83
	v_and_b32_e32 v229, 0xffff0000, v83
	v_lshlrev_b32_e32 v230, 16, v84
	v_and_b32_e32 v231, 0xffff0000, v84
	v_lshlrev_b32_e32 v232, 16, v85
	v_and_b32_e32 v233, 0xffff0000, v85
	v_pk_fma_f32 v[6:7], v[6:7], v[158:159], v[226:227]
	v_pk_fma_f32 v[8:9], v[8:9], v[160:161], v[228:229]
	v_pk_fma_f32 v[2:3], v[2:3], v[196:197], v[230:231]
	v_pk_fma_f32 v[4:5], v[4:5], v[198:199], v[232:233]
	v_cvt_pk_bf16_f32 v6, v6, v7
	v_cvt_pk_bf16_f32 v7, v8, v9
	v_cvt_pk_bf16_f32 v8, v2, v3
	v_cvt_pk_bf16_f32 v9, v4, v5
	global_store_dwordx4 v0, v[6:9], s[100:101] offset:256
	s_andn2_b64 vcc, exec, s[10:11]
	s_mov_b64 s[10:11], -1
	s_cbranch_vccnz .LBB0_1013

.LBB0_1223:
	s_ashr_i32 s11, s38, 3
	s_mul_hi_i32 s18, s11, 0xc000
	s_mul_i32 s11, s11, 0xc000
	s_add_u32 s11, s40, s11
	s_addc_u32 s22, s41, s18
	s_lshl_b32 s18, s39, 8
	s_ashr_i32 s19, s18, 31
	s_lshl_b64 s[20:21], s[18:19], 2
	s_add_u32 s20, s11, s20
	s_addc_u32 s21, s22, s21
	s_lshl_b32 s22, s38, 8
	s_ashr_i32 s23, s22, 31
	s_lshl_b64 s[22:23], s[22:23], 11
	s_add_u32 s18, s22, s18
	s_addc_u32 s19, s23, s19
	v_mov_b32_e32 v0, v147
	v_mov_b32_e32 v142, v146
	s_lshl_b64 s[18:19], s[18:19], 1
	s_add_u32 s38, s36, s18
	v_lshl_add_u32 v144, v142, 3, s49
	v_lshl_add_u32 v150, v0, 11, s56
	v_add_u32_e32 v0, v144, v150
	s_addc_u32 s39, s37, s19
	v_ashrrev_i32_e32 v145, 31, v144
	v_lshlrev_b64 v[160:161], 1, v[0:1]
	v_lshl_add_u64 v[142:143], v[144:145], 2, s[20:21]
	v_lshl_add_u64 v[168:169], s[38:39], 0, v[160:161]
	s_add_u32 s18, s46, s18
	s_addc_u32 s19, s47, s19
	s_andn2_b64 vcc, exec, s[12:13]
	v_lshlrev_b32_e32 v0, 1, v0
	global_load_dwordx4 v[150:153], v[142:143], off
	global_load_dwordx4 v[154:157], v[142:143], off offset:16
	global_load_dwordx4 v[158:161], v[142:143], off offset:512
	global_load_dwordx4 v[196:199], v[142:143], off offset:528
	s_add_u32 s98, s38, 0x0
	s_addc_u32 s99, s39, 0
	global_load_dwordx4 v[168:171], v0, s[98:99]
	s_add_u32 s98, s38, 0x0
	s_addc_u32 s99, s39, 0
	global_load_dwordx4 v[172:175], v0, s[98:99] offset:256
	s_add_u32 s98, s38, 0x10000
	s_addc_u32 s99, s39, 0
	global_load_dwordx4 v[176:179], v0, s[98:99]
	s_add_u32 s98, s38, 0x10000
	s_addc_u32 s99, s39, 0
	global_load_dwordx4 v[182:185], v0, s[98:99] offset:256
	s_add_u32 s98, s38, 0x20000
	s_addc_u32 s99, s39, 0
	global_load_dwordx4 v[186:189], v0, s[98:99]
	s_add_u32 s98, s38, 0x20000
	s_addc_u32 s99, s39, 0
	global_load_dwordx4 v[190:193], v0, s[98:99] offset:256
	s_add_u32 s98, s38, 0x30000
	s_addc_u32 s99, s39, 0
	global_load_dwordx4 v[204:207], v0, s[98:99]
	s_add_u32 s98, s38, 0x30000
	s_addc_u32 s99, s39, 0
	global_load_dwordx4 v[208:211], v0, s[98:99] offset:256
	s_add_u32 s98, s38, 0x80000
	s_addc_u32 s99, s39, 0
	global_load_dwordx4 v[216:219], v0, s[98:99]
	s_add_u32 s98, s38, 0x80000
	s_addc_u32 s99, s39, 0
	global_load_dwordx4 v[220:223], v0, s[98:99] offset:256
	s_waitcnt vmcnt(9)
	v_lshlrev_b32_e32 v226, 16, v168
	v_and_b32_e32 v227, 0xffff0000, v168
	v_lshlrev_b32_e32 v228, 16, v169
	v_and_b32_e32 v229, 0xffff0000, v169
	v_lshlrev_b32_e32 v230, 16, v170
	v_and_b32_e32 v231, 0xffff0000, v170
	v_lshlrev_b32_e32 v232, 16, v171
	v_and_b32_e32 v233, 0xffff0000, v171
	v_pk_fma_f32 v[126:127], v[126:127], v[150:151], v[226:227]
	v_pk_fma_f32 v[128:129], v[128:129], v[152:153], v[228:229]
	v_pk_fma_f32 v[122:123], v[122:123], v[154:155], v[230:231]
	v_pk_fma_f32 v[124:125], v[124:125], v[156:157], v[232:233]
	v_cvt_pk_bf16_f32 v126, v126, v127
	v_cvt_pk_bf16_f32 v127, v128, v129
	v_cvt_pk_bf16_f32 v128, v122, v123
	v_cvt_pk_bf16_f32 v129, v124, v125
	s_add_u32 s100, s18, 0x0
	s_addc_u32 s101, s19, 0
	global_store_dwordx4 v0, v[126:129], s[100:101]
	s_add_u32 s98, s38, 0x90000
	s_addc_u32 s99, s39, 0
	global_load_dwordx4 v[122:125], v0, s[98:99]
	s_waitcnt vmcnt(10)
	v_lshlrev_b32_e32 v226, 16, v172
	v_and_b32_e32 v227, 0xffff0000, v172
	v_lshlrev_b32_e32 v228, 16, v173
	v_and_b32_e32 v229, 0xffff0000, v173
	v_lshlrev_b32_e32 v230, 16, v174
	v_and_b32_e32 v231, 0xffff0000, v174
	v_lshlrev_b32_e32 v232, 16, v175
	v_and_b32_e32 v233, 0xffff0000, v175
	v_pk_fma_f32 v[118:119], v[118:119], v[158:159], v[226:227]
	v_pk_fma_f32 v[120:121], v[120:121], v[160:161], v[228:229]
	v_pk_fma_f32 v[114:115], v[114:115], v[196:197], v[230:231]
	v_pk_fma_f32 v[116:117], v[116:117], v[198:199], v[232:233]
	v_cvt_pk_bf16_f32 v118, v118, v119
	v_cvt_pk_bf16_f32 v119, v120, v121
	v_cvt_pk_bf16_f32 v120, v114, v115
	v_cvt_pk_bf16_f32 v121, v116, v117
	global_store_dwordx4 v0, v[118:121], s[100:101] offset:256
	s_add_u32 s98, s38, 0x90000
	s_addc_u32 s99, s39, 0
	global_load_dwordx4 v[114:117], v0, s[98:99] offset:256
	s_waitcnt vmcnt(11)
	v_lshlrev_b32_e32 v226, 16, v176
	v_and_b32_e32 v227, 0xffff0000, v176
	v_lshlrev_b32_e32 v228, 16, v177
	v_and_b32_e32 v229, 0xffff0000, v177
	v_lshlrev_b32_e32 v230, 16, v178
	v_and_b32_e32 v231, 0xffff0000, v178
	v_lshlrev_b32_e32 v232, 16, v179
	v_and_b32_e32 v233, 0xffff0000, v179
	v_pk_fma_f32 v[110:111], v[110:111], v[150:151], v[226:227]
	v_pk_fma_f32 v[112:113], v[112:113], v[152:153], v[228:229]
	v_pk_fma_f32 v[106:107], v[106:107], v[154:155], v[230:231]
	v_pk_fma_f32 v[108:109], v[108:109], v[156:157], v[232:233]
	v_cvt_pk_bf16_f32 v110, v110, v111
	v_cvt_pk_bf16_f32 v111, v112, v113
	v_cvt_pk_bf16_f32 v112, v106, v107
	v_cvt_pk_bf16_f32 v113, v108, v109
	s_add_u32 s100, s18, 0x10000
	s_addc_u32 s101, s19, 0
	global_store_dwordx4 v0, v[110:113], s[100:101]
	s_add_u32 s98, s38, 0xa0000
	s_addc_u32 s99, s39, 0
	global_load_dwordx4 v[106:109], v0, s[98:99]
	s_waitcnt vmcnt(12)
	v_lshlrev_b32_e32 v226, 16, v182
	v_and_b32_e32 v227, 0xffff0000, v182
	v_lshlrev_b32_e32 v228, 16, v183
	v_and_b32_e32 v229, 0xffff0000, v183
	v_lshlrev_b32_e32 v230, 16, v184
	v_and_b32_e32 v231, 0xffff0000, v184
	v_lshlrev_b32_e32 v232, 16, v185
	v_and_b32_e32 v233, 0xffff0000, v185
	v_pk_fma_f32 v[102:103], v[102:103], v[158:159], v[226:227]
	v_pk_fma_f32 v[104:105], v[104:105], v[160:161], v[228:229]
	v_pk_fma_f32 v[98:99], v[98:99], v[196:197], v[230:231]
	v_pk_fma_f32 v[100:101], v[100:101], v[198:199], v[232:233]
	v_cvt_pk_bf16_f32 v102, v102, v103
	v_cvt_pk_bf16_f32 v103, v104, v105
	v_cvt_pk_bf16_f32 v104, v98, v99
	v_cvt_pk_bf16_f32 v105, v100, v101
	global_store_dwordx4 v0, v[102:105], s[100:101] offset:256
	s_add_u32 s98, s38, 0xa0000
	s_addc_u32 s99, s39, 0
	global_load_dwordx4 v[98:101], v0, s[98:99] offset:256
	s_waitcnt vmcnt(13)
	v_lshlrev_b32_e32 v226, 16, v186
	v_and_b32_e32 v227, 0xffff0000, v186
	v_lshlrev_b32_e32 v228, 16, v187
	v_and_b32_e32 v229, 0xffff0000, v187
	v_lshlrev_b32_e32 v230, 16, v188
	v_and_b32_e32 v231, 0xffff0000, v188
	v_lshlrev_b32_e32 v232, 16, v189
	v_and_b32_e32 v233, 0xffff0000, v189
	v_pk_fma_f32 v[94:95], v[94:95], v[150:151], v[226:227]
	v_pk_fma_f32 v[96:97], v[96:97], v[152:153], v[228:229]
	v_pk_fma_f32 v[90:91], v[90:91], v[154:155], v[230:231]
	v_pk_fma_f32 v[92:93], v[92:93], v[156:157], v[232:233]
	v_cvt_pk_bf16_f32 v94, v94, v95
	v_cvt_pk_bf16_f32 v95, v96, v97
	v_cvt_pk_bf16_f32 v96, v90, v91
	v_cvt_pk_bf16_f32 v97, v92, v93
	s_add_u32 s100, s18, 0x20000
	s_addc_u32 s101, s19, 0
	global_store_dwordx4 v0, v[94:97], s[100:101]
	s_add_u32 s98, s38, 0xb0000
	s_addc_u32 s99, s39, 0
	global_load_dwordx4 v[90:93], v0, s[98:99]
	s_waitcnt vmcnt(14)
	v_lshlrev_b32_e32 v226, 16, v190
	v_and_b32_e32 v227, 0xffff0000, v190
	v_lshlrev_b32_e32 v228, 16, v191
	v_and_b32_e32 v229, 0xffff0000, v191
	v_lshlrev_b32_e32 v230, 16, v192
	v_and_b32_e32 v231, 0xffff0000, v192
	v_lshlrev_b32_e32 v232, 16, v193
	v_and_b32_e32 v233, 0xffff0000, v193
	v_pk_fma_f32 v[86:87], v[86:87], v[158:159], v[226:227]
	v_pk_fma_f32 v[88:89], v[88:89], v[160:161], v[228:229]
	v_pk_fma_f32 v[82:83], v[82:83], v[196:197], v[230:231]
	v_pk_fma_f32 v[84:85], v[84:85], v[198:199], v[232:233]
	v_cvt_pk_bf16_f32 v86, v86, v87
	v_cvt_pk_bf16_f32 v87, v88, v89
	v_cvt_pk_bf16_f32 v88, v82, v83
	v_cvt_pk_bf16_f32 v89, v84, v85
	global_store_dwordx4 v0, v[86:89], s[100:101] offset:256
	s_add_u32 s98, s38, 0xb0000
	s_addc_u32 s99, s39, 0
	global_load_dwordx4 v[82:85], v0, s[98:99] offset:256
	s_waitcnt vmcnt(15)
	v_lshlrev_b32_e32 v226, 16, v204
	v_and_b32_e32 v227, 0xffff0000, v204
	v_lshlrev_b32_e32 v228, 16, v205
	v_and_b32_e32 v229, 0xffff0000, v205
	v_lshlrev_b32_e32 v230, 16, v206
	v_and_b32_e32 v231, 0xffff0000, v206
	v_lshlrev_b32_e32 v232, 16, v207
	v_and_b32_e32 v233, 0xffff0000, v207
	v_pk_fma_f32 v[78:79], v[78:79], v[150:151], v[226:227]
	v_pk_fma_f32 v[80:81], v[80:81], v[152:153], v[228:229]
	v_pk_fma_f32 v[74:75], v[74:75], v[154:155], v[230:231]
	v_pk_fma_f32 v[76:77], v[76:77], v[156:157], v[232:233]
	v_cvt_pk_bf16_f32 v78, v78, v79
	v_cvt_pk_bf16_f32 v79, v80, v81
	v_cvt_pk_bf16_f32 v80, v74, v75
	v_cvt_pk_bf16_f32 v81, v76, v77
	s_add_u32 s100, s18, 0x30000
	s_addc_u32 s101, s19, 0
	global_store_dwordx4 v0, v[78:81], s[100:101]
	s_waitcnt vmcnt(15)
	v_lshlrev_b32_e32 v226, 16, v208
	v_and_b32_e32 v227, 0xffff0000, v208
	v_lshlrev_b32_e32 v228, 16, v209
	v_and_b32_e32 v229, 0xffff0000, v209
	v_lshlrev_b32_e32 v230, 16, v210
	v_and_b32_e32 v231, 0xffff0000, v210
	v_lshlrev_b32_e32 v232, 16, v211
	v_and_b32_e32 v233, 0xffff0000, v211
	v_pk_fma_f32 v[70:71], v[70:71], v[158:159], v[226:227]
	v_pk_fma_f32 v[72:73], v[72:73], v[160:161], v[228:229]
	v_pk_fma_f32 v[66:67], v[66:67], v[196:197], v[230:231]
	v_pk_fma_f32 v[68:69], v[68:69], v[198:199], v[232:233]
	v_cvt_pk_bf16_f32 v70, v70, v71
	v_cvt_pk_bf16_f32 v71, v72, v73
	v_cvt_pk_bf16_f32 v72, v66, v67
	v_cvt_pk_bf16_f32 v73, v68, v69
	global_store_dwordx4 v0, v[70:73], s[100:101] offset:256
	s_waitcnt vmcnt(15)
	v_lshlrev_b32_e32 v226, 16, v216
	v_and_b32_e32 v227, 0xffff0000, v216
	v_lshlrev_b32_e32 v228, 16, v217
	v_and_b32_e32 v229, 0xffff0000, v217
	v_lshlrev_b32_e32 v230, 16, v218
	v_and_b32_e32 v231, 0xffff0000, v218
	v_lshlrev_b32_e32 v232, 16, v219
	v_and_b32_e32 v233, 0xffff0000, v219
	v_pk_fma_f32 v[62:63], v[62:63], v[150:151], v[226:227]
	v_pk_fma_f32 v[64:65], v[64:65], v[152:153], v[228:229]
	v_pk_fma_f32 v[58:59], v[58:59], v[154:155], v[230:231]
	v_pk_fma_f32 v[60:61], v[60:61], v[156:157], v[232:233]
	v_cvt_pk_bf16_f32 v62, v62, v63
	v_cvt_pk_bf16_f32 v63, v64, v65
	v_cvt_pk_bf16_f32 v64, v58, v59
	v_cvt_pk_bf16_f32 v65, v60, v61
	s_add_u32 s100, s18, 0x80000
	s_addc_u32 s101, s19, 0
	global_store_dwordx4 v0, v[62:65], s[100:101]
	s_waitcnt vmcnt(15)
	v_lshlrev_b32_e32 v226, 16, v220
	v_and_b32_e32 v227, 0xffff0000, v220
	v_lshlrev_b32_e32 v228, 16, v221
	v_and_b32_e32 v229, 0xffff0000, v221
	v_lshlrev_b32_e32 v230, 16, v222
	v_and_b32_e32 v231, 0xffff0000, v222
	v_lshlrev_b32_e32 v232, 16, v223
	v_and_b32_e32 v233, 0xffff0000, v223
	v_pk_fma_f32 v[54:55], v[54:55], v[158:159], v[226:227]
	v_pk_fma_f32 v[56:57], v[56:57], v[160:161], v[228:229]
	v_pk_fma_f32 v[50:51], v[50:51], v[196:197], v[230:231]
	v_pk_fma_f32 v[52:53], v[52:53], v[198:199], v[232:233]
	v_cvt_pk_bf16_f32 v54, v54, v55
	v_cvt_pk_bf16_f32 v55, v56, v57
	v_cvt_pk_bf16_f32 v56, v50, v51
	v_cvt_pk_bf16_f32 v57, v52, v53
	global_store_dwordx4 v0, v[54:57], s[100:101] offset:256
	s_waitcnt vmcnt(14)
	v_lshlrev_b32_e32 v226, 16, v122
	v_and_b32_e32 v227, 0xffff0000, v122
	v_lshlrev_b32_e32 v228, 16, v123
	v_and_b32_e32 v229, 0xffff0000, v123
	v_lshlrev_b32_e32 v230, 16, v124
	v_and_b32_e32 v231, 0xffff0000, v124
	v_lshlrev_b32_e32 v232, 16, v125
	v_and_b32_e32 v233, 0xffff0000, v125
	v_pk_fma_f32 v[46:47], v[46:47], v[150:151], v[226:227]
	v_pk_fma_f32 v[48:49], v[48:49], v[152:153], v[228:229]
	v_pk_fma_f32 v[42:43], v[42:43], v[154:155], v[230:231]
	v_pk_fma_f32 v[44:45], v[44:45], v[156:157], v[232:233]
	v_cvt_pk_bf16_f32 v46, v46, v47
	v_cvt_pk_bf16_f32 v47, v48, v49
	v_cvt_pk_bf16_f32 v48, v42, v43
	v_cvt_pk_bf16_f32 v49, v44, v45
	s_add_u32 s100, s18, 0x90000
	s_addc_u32 s101, s19, 0
	global_store_dwordx4 v0, v[46:49], s[100:101]
	s_waitcnt vmcnt(13)
	v_lshlrev_b32_e32 v226, 16, v114
	v_and_b32_e32 v227, 0xffff0000, v114
	v_lshlrev_b32_e32 v228, 16, v115
	v_and_b32_e32 v229, 0xffff0000, v115
	v_lshlrev_b32_e32 v230, 16, v116
	v_and_b32_e32 v231, 0xffff0000, v116
	v_lshlrev_b32_e32 v232, 16, v117
	v_and_b32_e32 v233, 0xffff0000, v117
	v_pk_fma_f32 v[38:39], v[38:39], v[158:159], v[226:227]
	v_pk_fma_f32 v[40:41], v[40:41], v[160:161], v[228:229]
	v_pk_fma_f32 v[34:35], v[34:35], v[196:197], v[230:231]
	v_pk_fma_f32 v[36:37], v[36:37], v[198:199], v[232:233]
	v_cvt_pk_bf16_f32 v38, v38, v39
	v_cvt_pk_bf16_f32 v39, v40, v41
	v_cvt_pk_bf16_f32 v40, v34, v35
	v_cvt_pk_bf16_f32 v41, v36, v37
	global_store_dwordx4 v0, v[38:41], s[100:101] offset:256
	s_waitcnt vmcnt(12)
	v_lshlrev_b32_e32 v226, 16, v106
	v_and_b32_e32 v227, 0xffff0000, v106
	v_lshlrev_b32_e32 v228, 16, v107
	v_and_b32_e32 v229, 0xffff0000, v107
	v_lshlrev_b32_e32 v230, 16, v108
	v_and_b32_e32 v231, 0xffff0000, v108
	v_lshlrev_b32_e32 v232, 16, v109
	v_and_b32_e32 v233, 0xffff0000, v109
	v_pk_fma_f32 v[30:31], v[30:31], v[150:151], v[226:227]
	v_pk_fma_f32 v[32:33], v[32:33], v[152:153], v[228:229]
	v_pk_fma_f32 v[26:27], v[26:27], v[154:155], v[230:231]
	v_pk_fma_f32 v[28:29], v[28:29], v[156:157], v[232:233]
	v_cvt_pk_bf16_f32 v30, v30, v31
	v_cvt_pk_bf16_f32 v31, v32, v33
	v_cvt_pk_bf16_f32 v32, v26, v27
	v_cvt_pk_bf16_f32 v33, v28, v29
	s_add_u32 s100, s18, 0xa0000
	s_addc_u32 s101, s19, 0
	global_store_dwordx4 v0, v[30:33], s[100:101]
	s_waitcnt vmcnt(11)
	v_lshlrev_b32_e32 v226, 16, v98
	v_and_b32_e32 v227, 0xffff0000, v98
	v_lshlrev_b32_e32 v228, 16, v99
	v_and_b32_e32 v229, 0xffff0000, v99
	v_lshlrev_b32_e32 v230, 16, v100
	v_and_b32_e32 v231, 0xffff0000, v100
	v_lshlrev_b32_e32 v232, 16, v101
	v_and_b32_e32 v233, 0xffff0000, v101
	v_pk_fma_f32 v[22:23], v[22:23], v[158:159], v[226:227]
	v_pk_fma_f32 v[24:25], v[24:25], v[160:161], v[228:229]
	v_pk_fma_f32 v[18:19], v[18:19], v[196:197], v[230:231]
	v_pk_fma_f32 v[20:21], v[20:21], v[198:199], v[232:233]
	v_cvt_pk_bf16_f32 v22, v22, v23
	v_cvt_pk_bf16_f32 v23, v24, v25
	v_cvt_pk_bf16_f32 v24, v18, v19
	v_cvt_pk_bf16_f32 v25, v20, v21
	global_store_dwordx4 v0, v[22:25], s[100:101] offset:256
	s_waitcnt vmcnt(10)
	v_lshlrev_b32_e32 v226, 16, v90
	v_and_b32_e32 v227, 0xffff0000, v90
	v_lshlrev_b32_e32 v228, 16, v91
	v_and_b32_e32 v229, 0xffff0000, v91
	v_lshlrev_b32_e32 v230, 16, v92
	v_and_b32_e32 v231, 0xffff0000, v92
	v_lshlrev_b32_e32 v232, 16, v93
	v_and_b32_e32 v233, 0xffff0000, v93
	v_pk_fma_f32 v[14:15], v[14:15], v[150:151], v[226:227]
	v_pk_fma_f32 v[16:17], v[16:17], v[152:153], v[228:229]
	v_pk_fma_f32 v[10:11], v[10:11], v[154:155], v[230:231]
	v_pk_fma_f32 v[12:13], v[12:13], v[156:157], v[232:233]
	v_cvt_pk_bf16_f32 v14, v14, v15
	v_cvt_pk_bf16_f32 v15, v16, v17
	v_cvt_pk_bf16_f32 v16, v10, v11
	v_cvt_pk_bf16_f32 v17, v12, v13
	s_add_u32 s100, s18, 0xb0000
	s_addc_u32 s101, s19, 0
	global_store_dwordx4 v0, v[14:17], s[100:101]
	s_waitcnt vmcnt(9)
	v_lshlrev_b32_e32 v226, 16, v82
	v_and_b32_e32 v227, 0xffff0000, v82
	v_lshlrev_b32_e32 v228, 16, v83
	v_and_b32_e32 v229, 0xffff0000, v83
	v_lshlrev_b32_e32 v230, 16, v84
	v_and_b32_e32 v231, 0xffff0000, v84
	v_lshlrev_b32_e32 v232, 16, v85
	v_and_b32_e32 v233, 0xffff0000, v85
	v_pk_fma_f32 v[6:7], v[6:7], v[158:159], v[226:227]
	v_pk_fma_f32 v[8:9], v[8:9], v[160:161], v[228:229]
	v_pk_fma_f32 v[2:3], v[2:3], v[196:197], v[230:231]
	v_pk_fma_f32 v[4:5], v[4:5], v[198:199], v[232:233]
	v_cvt_pk_bf16_f32 v6, v6, v7
	v_cvt_pk_bf16_f32 v7, v8, v9
	v_cvt_pk_bf16_f32 v8, v2, v3
	v_cvt_pk_bf16_f32 v9, v4, v5
	global_store_dwordx4 v0, v[6:9], s[100:101] offset:256
	s_mov_b64 s[18:19], -1
	s_cbranch_vccnz .LBB0_1212
	s_andn2_b64 vcc, exec, s[4:5]
	s_cbranch_vccnz .LBB0_1211
	s_barrier
	s_branch .LBB0_1211
